# a_w_out conversion moved from phase 0 (exposed) to the idle tail of the layer-0 in-proj GEMM
# baseline (speedup 1.0000x reference)
.LBB0_17:
	v_mov_b32_e32 v8, v182
	s_lshl_b32 s6, s2, 3
	v_readfirstlane_b32 s4, v8
	s_ashr_i32 s7, s4, 6
	s_load_dwordx2 s[4:5], s[0:1], 0xa8
	s_lshl_b32 s40, s38, 3
	v_and_b32_e32 v1, 63, v8
	v_writelane_b32 v249, s6, 2
	s_add_i32 s6, s7, s6
	s_cmpk_gt_i32 s6, 0x17ff
	v_lshlrev_b32_e32 v0, 3, v1
	s_cbranch_scc1 .LBB0_32
	s_mul_i32 s8, s7, 0x2100
	v_lshrrev_b32_e32 v27, 3, v1
	v_and_b32_e32 v2, 56, v0
	s_add_i32 s10, s8, 0
	v_mul_u32_u24_e32 v3, 0x84, v2
	v_lshlrev_b32_e32 v4, 2, v27
	v_lshrrev_b32_e32 v26, 5, v1
	v_add3_u32 v28, s10, v3, v4
	v_lshlrev_b32_e32 v2, 1, v2
	v_mov_b32_e32 v3, 0
	s_waitcnt lgkmcnt(0)
	v_lshl_add_u64 v[4:5], s[4:5], 0, v[2:3]
	v_mul_u32_u24_e32 v2, 0x84, v26
	v_lshlrev_b32_e32 v8, 2, v8
	s_mov_b64 s[10:11], 0x1800000
	v_or_b32_e32 v2, s8, v2
	v_and_b32_e32 v8, 0x7c, v8
	s_lshl_b32 s8, s2, 8
	s_lshl_b32 s7, s7, 5
	s_mov_b32 s9, 0
	v_or_b32_e32 v29, 8, v27
	v_or_b32_e32 v30, 16, v27
	v_or_b32_e32 v31, 24, v27
	v_lshl_add_u64 v[6:7], v[4:5], 0, s[10:11]
	v_add3_u32 v32, v2, v8, 0
	v_mov_b32_e32 v9, v3
	s_add_i32 s7, s8, s7
	s_lshl_b32 s14, s38, 8
	v_or_b32_e32 v33, 14, v26
	s_add_i32 s15, s6, 0xe800
	v_or_b32_e32 v34, 12, v26
	v_or_b32_e32 v35, 10, v26
	v_or_b32_e32 v36, 8, v26
	v_or_b32_e32 v37, 6, v26
	v_or_b32_e32 v38, 4, v26
	v_or_b32_e32 v39, 2, v26
	s_movk_i32 s16, 0x6000
	s_mov_b32 s17, s6
	s_branch .LBB0_20
.LBB0_19:
	s_add_i32 s17, s17, s40
	s_add_i32 s7, s7, s14
	s_add_i32 s15, s15, s40
	s_cmpk_lt_i32 s17, 0x1800
	s_cbranch_scc0 .LBB0_32

.LBB0_379:
	v_readlane_b32 s0, v249, 31
	v_readlane_b32 s1, v249, 32
	s_and_b64 vcc, exec, s[0:1]
	s_cbranch_vccz .LBB0_407
	v_mov_b32_e32 v6, v182
	v_readlane_b32 s1, v249, 34
	v_readfirstlane_b32 s0, v6
	s_ashr_i32 s0, s0, 6
	s_add_i32 s6, s1, s0
	s_addk_i32 s6, 0xf800
	s_cmpk_gt_i32 s6, 0x4bff
	s_cbranch_scc1 .LBB0_407
	v_lshlrev_b32_e32 v0, 3, v6
	s_mul_i32 s1, s0, 0x2100
	v_bfe_u32 v25, v6, 3, 3
	v_and_b32_e32 v0, 56, v0
	s_add_i32 s4, s1, 0
	v_bfe_u32 v24, v6, 5, 1
	v_mul_u32_u24_e32 v1, 0x84, v0
	v_lshlrev_b32_e32 v2, 2, v25
	v_lshlrev_b32_e32 v144, 1, v0
	v_add3_u32 v26, s4, v1, v2
	s_waitcnt lgkmcnt(0)
	v_lshl_add_u64 v[0:1], s[22:23], 0, v[144:145]
	s_mov_b64 s[4:5], 0x3800000
	v_mul_u32_u24_e32 v7, 0x84, v24
	v_lshlrev_b32_e32 v6, 2, v6
	v_lshl_add_u64 v[2:3], v[0:1], 0, s[4:5]
	s_mov_b64 s[4:5], 0x1800000
	v_or_b32_e32 v7, s1, v7
	v_and_b32_e32 v6, 0x7c, v6
	v_readlane_b32 s1, v249, 58
	v_or_b32_e32 v27, 8, v25
	v_or_b32_e32 v28, 16, v25
	v_or_b32_e32 v29, 24, v25
	v_lshl_add_u64 v[4:5], v[0:1], 0, s[4:5]
	v_add3_u32 v30, v7, v6, 0
	v_mov_b32_e32 v7, v145
	v_or_b32_e32 v31, 14, v24
	v_or_b32_e32 v32, 12, v24
	v_or_b32_e32 v33, 10, v24
	v_or_b32_e32 v34, 8, v24
	v_or_b32_e32 v35, 6, v24
	v_or_b32_e32 v36, 4, v24
	v_or_b32_e32 v37, 2, v24
	s_lshl_b32 s7, s6, 5
	s_add_i32 s8, s1, s0
	s_addk_i32 s8, 0xf800
	s_branch .LBB0_383
